# P1: row-sum reductions of the q/k epilogue by permlane16/32 swaps instead of LDS bpermute round trips; units 1 and 3 swapped between workgroup pairs so each gets two gate tiles
# speedup vs baseline: 1.0025x; 1.0025x over previous
; template <class Epi, class Sched, bool ALIGN_EPI = false, bool SP2 = false>
; __device__ __forceinline__ void gemm_phase(PG8_LAS unsigned char* lds, const Gemm g, const Sched& S, const Epi& E) {
;     ...
;     f32x4 acc[2][2][4][2];
; #pragma unroll
;     for (int a = 0; a < 2; ++a)
; #pragma unroll
;         for (int b = 0; b < 2; ++b)
; #pragma unroll
;             for (int m = 0; m < 4; ++m)
; #pragma unroll
;                 for (int n = 0; n < 2; ++n) acc[a][b][m][n] = (f32x4){0.f, 0.f, 0.f, 0.f};
;     bf16x8 At[4][2], B0[2][2], B1[2][2];
;     const char* cA = (const char*)(g.A + (size_t)cur.g * g.gsA) + (size_t)cur.pm * tstepA; const char* cB = (const char*)(g.Bt + (size_t)cur.g * g.gsB) + (size_t)cur.pn * tstepB;
.LBB0_84:
	s_lshl_b32 s32, s63, 4
	s_and_b32 s32, s32, 16
	s_xor_b32 s22, s22, s32
	s_ashr_i32 s25, s24, 31
	s_lshl_b64 s[26:27], s[24:25], 20
	s_add_u32 s26, s37, s26
	s_addc_u32 s27, s38, s27
	s_ashr_i32 s23, s22, 31
	s_lshl_b64 s[28:29], s[22:23], 20
	s_add_u32 s28, s39, s28
	v_mov_b32_e32 v127, 0
	s_addc_u32 s29, s44, s29
	s_and_b64 vcc, exec, s[6:7]
	v_mov_b32_e32 v126, v127
	v_mov_b32_e32 v125, v127
	v_mov_b32_e32 v124, v127
	v_mov_b32_e32 v123, v127
	v_mov_b32_e32 v122, v127
	v_mov_b32_e32 v121, v127
	v_mov_b32_e32 v120, v127
	v_mov_b32_e32 v111, v127
	v_mov_b32_e32 v110, v127
	v_mov_b32_e32 v109, v127
	v_mov_b32_e32 v108, v127
	v_mov_b32_e32 v107, v127
	v_mov_b32_e32 v106, v127
	v_mov_b32_e32 v105, v127
	v_mov_b32_e32 v104, v127
	v_mov_b32_e32 v95, v127
	v_mov_b32_e32 v94, v127
	v_mov_b32_e32 v93, v127
	v_mov_b32_e32 v92, v127
	v_mov_b32_e32 v91, v127
	v_mov_b32_e32 v90, v127
	v_mov_b32_e32 v89, v127
	v_mov_b32_e32 v88, v127
	v_mov_b32_e32 v79, v127
	v_mov_b32_e32 v78, v127
	v_mov_b32_e32 v77, v127
	v_mov_b32_e32 v76, v127
	v_mov_b32_e32 v75, v127
	v_mov_b32_e32 v74, v127
	v_mov_b32_e32 v73, v127
	v_mov_b32_e32 v72, v127
	v_mov_b32_e32 v119, v127
	v_mov_b32_e32 v118, v127
	v_mov_b32_e32 v117, v127
	v_mov_b32_e32 v116, v127
	v_mov_b32_e32 v115, v127
	v_mov_b32_e32 v114, v127
	v_mov_b32_e32 v113, v127
	v_mov_b32_e32 v112, v127
	v_mov_b32_e32 v103, v127
	v_mov_b32_e32 v102, v127
	v_mov_b32_e32 v101, v127
	v_mov_b32_e32 v100, v127
	v_mov_b32_e32 v99, v127
	v_mov_b32_e32 v98, v127
	v_mov_b32_e32 v97, v127
	v_mov_b32_e32 v96, v127
	v_mov_b32_e32 v87, v127
	v_mov_b32_e32 v86, v127
	v_mov_b32_e32 v85, v127
	v_mov_b32_e32 v84, v127
	v_mov_b32_e32 v83, v127
	v_mov_b32_e32 v82, v127
	v_mov_b32_e32 v81, v127
	v_mov_b32_e32 v80, v127
	v_mov_b32_e32 v71, v127
	v_mov_b32_e32 v70, v127
	v_mov_b32_e32 v69, v127
	v_mov_b32_e32 v68, v127
	v_mov_b32_e32 v67, v127
	v_mov_b32_e32 v66, v127
	v_mov_b32_e32 v65, v127
	v_mov_b32_e32 v64, v127
	v_mov_b32_e32 v63, v127
	v_mov_b32_e32 v62, v127
	v_mov_b32_e32 v61, v127
	v_mov_b32_e32 v60, v127
	v_mov_b32_e32 v59, v127
	v_mov_b32_e32 v58, v127
	v_mov_b32_e32 v57, v127
	v_mov_b32_e32 v56, v127
	v_mov_b32_e32 v47, v127
	v_mov_b32_e32 v46, v127
	v_mov_b32_e32 v45, v127
	v_mov_b32_e32 v44, v127
	v_mov_b32_e32 v43, v127
	v_mov_b32_e32 v42, v127
	v_mov_b32_e32 v41, v127
	v_mov_b32_e32 v40, v127
	v_mov_b32_e32 v31, v127
	v_mov_b32_e32 v30, v127
	v_mov_b32_e32 v29, v127
	v_mov_b32_e32 v28, v127
	v_mov_b32_e32 v27, v127
	v_mov_b32_e32 v26, v127
	v_mov_b32_e32 v25, v127
	v_mov_b32_e32 v24, v127
	v_mov_b32_e32 v15, v127
	v_mov_b32_e32 v14, v127
	v_mov_b32_e32 v13, v127
	v_mov_b32_e32 v12, v127
	v_mov_b32_e32 v11, v127
	v_mov_b32_e32 v10, v127
	v_mov_b32_e32 v9, v127
	v_mov_b32_e32 v8, v127
	v_mov_b32_e32 v55, v127
	v_mov_b32_e32 v54, v127
	v_mov_b32_e32 v53, v127
	v_mov_b32_e32 v52, v127
	v_mov_b32_e32 v51, v127
	v_mov_b32_e32 v50, v127
	v_mov_b32_e32 v49, v127
	v_mov_b32_e32 v48, v127
	v_mov_b32_e32 v39, v127
	v_mov_b32_e32 v38, v127
	v_mov_b32_e32 v37, v127
	v_mov_b32_e32 v36, v127
	v_mov_b32_e32 v35, v127
	v_mov_b32_e32 v34, v127
	v_mov_b32_e32 v33, v127
	v_mov_b32_e32 v32, v127
	v_mov_b32_e32 v23, v127
	v_mov_b32_e32 v22, v127
	v_mov_b32_e32 v21, v127
	v_mov_b32_e32 v20, v127
	v_mov_b32_e32 v19, v127
	v_mov_b32_e32 v18, v127
	v_mov_b32_e32 v17, v127
	v_mov_b32_e32 v16, v127
	v_mov_b32_e32 v7, v127
	v_mov_b32_e32 v6, v127
	v_mov_b32_e32 v5, v127
	v_mov_b32_e32 v4, v127
	v_mov_b32_e32 v3, v127
	v_mov_b32_e32 v2, v127
	s_waitcnt lgkmcnt(0)
	v_mov_b32_e32 v1, v127
	v_mov_b32_e32 v0, v127
	s_cbranch_vccnz .LBB0_87
	s_and_b64 s[34:35], s[8:9], exec
	s_cselect_b32 s11, s27, s31
	s_cselect_b32 s23, s26, s30
	s_cselect_b32 s25, s29, s13
	s_cselect_b32 s40, s28, s12
	s_add_u32 s41, s12, 0x100
	s_addc_u32 s42, s13, 0
	s_add_u32 s12, s30, 0x80080
	s_addc_u32 s13, s31, 0
	s_mov_b32 s30, 0

; __device__ __forceinline__ float sq4(const f32x4& v) { return (v[0] * v[0] + v[1] * v[1]) + (v[2] * v[2] + v[3] * v[3]); }
;     __device__ __forceinline__ void operator()(const f32x4 (&acc)[2][2][4][2], const Unit& u, int wr, int wc, int fr, int fq) const {
;     ...
;                 if (reg <= 1) { float s = sq4(v0) + sq4(v1); s += __shfl_xor(s, 16); s += __shfl_xor(s, 32); mx[bj] = fmaxf(mx[bj], s); }
.LBB0_96:
	v_mov_b32_e32 v122, v153
	v_mov_b32_e32 v123, v149
	v_mov_b32_e32 v120, v152
	v_mov_b32_e32 v121, v148
	v_pk_mul_f32 v[122:123], v[122:123], v[122:123]
	v_mov_b32_e32 v124, v155
	v_mov_b32_e32 v125, v151
	v_pk_fma_f32 v[120:121], v[120:121], v[120:121], v[122:123]
	v_mov_b32_e32 v122, v154
	v_mov_b32_e32 v123, v150
	v_pk_mul_f32 v[124:125], v[124:125], v[124:125]
	s_nop 0
	v_pk_fma_f32 v[122:123], v[122:123], v[122:123], v[124:125]
	s_nop 0
	v_pk_add_f32 v[120:121], v[120:121], v[122:123]
	v_and_b32_e32 v122, 64, v163
	v_add_f32_e32 v120, v120, v121
	v_xor_b32_e32 v121, 16, v163
	v_add_u32_e32 v122, 64, v122
	v_cmp_lt_i32_e32 vcc, v121, v122
	s_nop 1
	v_cndmask_b32_e32 v121, v163, v121, vcc
	v_lshlrev_b32_e32 v121, 2, v121
	v_mov_b32_e32 v121, v120
	s_nop 1
	v_permlane16_swap_b32_e32 v120, v121
	s_waitcnt lgkmcnt(0)
	v_add_f32_e32 v120, v120, v121
	v_xor_b32_e32 v121, 32, v163
	v_cmp_lt_i32_e32 vcc, v121, v122
	s_nop 1
	v_cndmask_b32_e32 v121, v163, v121, vcc
	v_lshlrev_b32_e32 v121, 2, v121
	v_mov_b32_e32 v121, v120
	s_nop 1
	v_permlane32_swap_b32_e32 v120, v121
	s_waitcnt lgkmcnt(0)
	v_add_f32_e32 v120, v120, v121
	v_max_f32_e32 v120, 0, v120
	v_mov_b32_e32 v121, v136
	s_branch .LBB0_100

; __device__ __forceinline__ float sq4(const f32x4& v) { return (v[0] * v[0] + v[1] * v[1]) + (v[2] * v[2] + v[3] * v[3]); }
;     __device__ __forceinline__ void operator()(const f32x4 (&acc)[2][2][4][2], const Unit& u, int wr, int wc, int fr, int fq) const {
;     ...
;                 if (reg <= 1) { float s = sq4(v0) + sq4(v1); s += __shfl_xor(s, 16); s += __shfl_xor(s, 32); mx[bj] = fmaxf(mx[bj], s); }
.LBB0_103:
	v_mov_b32_e32 v114, v151
	v_mov_b32_e32 v115, v127
	v_mov_b32_e32 v112, v150
	v_mov_b32_e32 v113, v126
	v_pk_mul_f32 v[114:115], v[114:115], v[114:115]
	v_mov_b32_e32 v116, v153
	v_mov_b32_e32 v117, v149
	v_pk_fma_f32 v[112:113], v[112:113], v[112:113], v[114:115]
	v_mov_b32_e32 v114, v152
	v_mov_b32_e32 v115, v148
	v_pk_mul_f32 v[116:117], v[116:117], v[116:117]
	s_nop 0
	v_pk_fma_f32 v[114:115], v[114:115], v[114:115], v[116:117]
	s_nop 0
	v_pk_add_f32 v[112:113], v[112:113], v[114:115]
	v_and_b32_e32 v114, 64, v163
	v_add_f32_e32 v112, v112, v113
	v_xor_b32_e32 v113, 16, v163
	v_add_u32_e32 v114, 64, v114
	v_cmp_lt_i32_e32 vcc, v113, v114
	s_nop 1
	v_cndmask_b32_e32 v113, v163, v113, vcc
	v_lshlrev_b32_e32 v113, 2, v113
	v_mov_b32_e32 v113, v112
	s_nop 1
	v_permlane16_swap_b32_e32 v112, v113
	s_waitcnt lgkmcnt(0)
	v_add_f32_e32 v112, v112, v113
	v_xor_b32_e32 v113, 32, v163
	v_cmp_lt_i32_e32 vcc, v113, v114
	s_nop 1
	v_cndmask_b32_e32 v113, v163, v113, vcc
	v_lshlrev_b32_e32 v113, 2, v113
	v_mov_b32_e32 v113, v112
	s_nop 1
	v_permlane32_swap_b32_e32 v112, v113
	s_waitcnt lgkmcnt(0)
	v_add_f32_e32 v112, v112, v113
	v_max_f32_e32 v113, v121, v121
	v_max_f32_e32 v121, v113, v112

; __device__ __forceinline__ float sq4(const f32x4& v) { return (v[0] * v[0] + v[1] * v[1]) + (v[2] * v[2] + v[3] * v[3]); }
;     __device__ __forceinline__ void operator()(const f32x4 (&acc)[2][2][4][2], const Unit& u, int wr, int wc, int fr, int fq) const {
;     ...
;                 if (reg <= 1) { float s = sq4(v0) + sq4(v1); s += __shfl_xor(s, 16); s += __shfl_xor(s, 32); mx[bj] = fmaxf(mx[bj], s); }
.LBB0_107:
	v_mov_b32_e32 v106, v117
	v_mov_b32_e32 v107, v113
	v_mov_b32_e32 v104, v116
	v_mov_b32_e32 v105, v112
	v_pk_mul_f32 v[106:107], v[106:107], v[106:107]
	v_mov_b32_e32 v108, v119
	v_mov_b32_e32 v109, v115
	v_pk_fma_f32 v[104:105], v[104:105], v[104:105], v[106:107]
	v_mov_b32_e32 v106, v118
	v_mov_b32_e32 v107, v114
	v_pk_mul_f32 v[108:109], v[108:109], v[108:109]
	s_nop 0
	v_pk_fma_f32 v[106:107], v[106:107], v[106:107], v[108:109]
	s_nop 0
	v_pk_add_f32 v[104:105], v[104:105], v[106:107]
	v_and_b32_e32 v106, 64, v163
	v_add_f32_e32 v104, v104, v105
	v_xor_b32_e32 v105, 16, v163
	v_add_u32_e32 v106, 64, v106
	v_cmp_lt_i32_e32 vcc, v105, v106
	s_nop 1
	v_cndmask_b32_e32 v105, v163, v105, vcc
	v_lshlrev_b32_e32 v105, 2, v105
	v_mov_b32_e32 v105, v104
	s_nop 1
	v_permlane16_swap_b32_e32 v104, v105
	s_waitcnt lgkmcnt(0)
	v_add_f32_e32 v104, v104, v105
	v_xor_b32_e32 v105, 32, v163
	v_cmp_lt_i32_e32 vcc, v105, v106
	s_nop 1
	v_cndmask_b32_e32 v105, v163, v105, vcc
	v_lshlrev_b32_e32 v105, 2, v105
	v_mov_b32_e32 v105, v104
	s_nop 1
	v_permlane32_swap_b32_e32 v104, v105
	s_waitcnt lgkmcnt(0)
	v_add_f32_e32 v104, v104, v105
	v_max_f32_e32 v105, v120, v120
	v_max_f32_e32 v120, v105, v104

; __device__ __forceinline__ float sq4(const f32x4& v) { return (v[0] * v[0] + v[1] * v[1]) + (v[2] * v[2] + v[3] * v[3]); }
;     __device__ __forceinline__ void operator()(const f32x4 (&acc)[2][2][4][2], const Unit& u, int wr, int wc, int fr, int fq) const {
;     ...
;                 if (reg <= 1) { float s = sq4(v0) + sq4(v1); s += __shfl_xor(s, 16); s += __shfl_xor(s, 32); mx[bj] = fmaxf(mx[bj], s); }
.LBB0_111:
	v_mov_b32_e32 v98, v111
	v_mov_b32_e32 v99, v107
	v_mov_b32_e32 v96, v110
	v_mov_b32_e32 v97, v106
	v_pk_mul_f32 v[98:99], v[98:99], v[98:99]
	v_mov_b32_e32 v100, v113
	v_mov_b32_e32 v101, v109
	v_pk_fma_f32 v[96:97], v[96:97], v[96:97], v[98:99]
	v_mov_b32_e32 v98, v112
	v_mov_b32_e32 v99, v108
	v_pk_mul_f32 v[100:101], v[100:101], v[100:101]
	s_nop 0
	v_pk_fma_f32 v[98:99], v[98:99], v[98:99], v[100:101]
	s_nop 0
	v_pk_add_f32 v[96:97], v[96:97], v[98:99]
	v_and_b32_e32 v98, 64, v163
	v_add_f32_e32 v96, v96, v97
	v_xor_b32_e32 v97, 16, v163
	v_add_u32_e32 v98, 64, v98
	v_cmp_lt_i32_e32 vcc, v97, v98
	s_nop 1
	v_cndmask_b32_e32 v97, v163, v97, vcc
	v_lshlrev_b32_e32 v97, 2, v97
	v_mov_b32_e32 v97, v96
	s_nop 1
	v_permlane16_swap_b32_e32 v96, v97
	s_waitcnt lgkmcnt(0)
	v_add_f32_e32 v96, v96, v97
	v_xor_b32_e32 v97, 32, v163
	v_cmp_lt_i32_e32 vcc, v97, v98
	s_nop 1
	v_cndmask_b32_e32 v97, v163, v97, vcc
	v_lshlrev_b32_e32 v97, 2, v97
	v_mov_b32_e32 v97, v96
	s_nop 1
	v_permlane32_swap_b32_e32 v96, v97
	s_waitcnt lgkmcnt(0)
	v_add_f32_e32 v96, v96, v97
	v_max_f32_e32 v97, v121, v121
	v_max_f32_e32 v121, v97, v96

; __device__ __forceinline__ float sq4(const f32x4& v) { return (v[0] * v[0] + v[1] * v[1]) + (v[2] * v[2] + v[3] * v[3]); }
;     __device__ __forceinline__ void operator()(const f32x4 (&acc)[2][2][4][2], const Unit& u, int wr, int wc, int fr, int fq) const {
;     ...
;                 if (reg <= 1) { float s = sq4(v0) + sq4(v1); s += __shfl_xor(s, 16); s += __shfl_xor(s, 32); mx[bj] = fmaxf(mx[bj], s); }
.LBB0_115:
	v_mov_b32_e32 v90, v101
	v_mov_b32_e32 v91, v97
	v_mov_b32_e32 v88, v100
	v_mov_b32_e32 v89, v96
	v_pk_mul_f32 v[90:91], v[90:91], v[90:91]
	v_mov_b32_e32 v92, v103
	v_mov_b32_e32 v93, v99
	v_pk_fma_f32 v[88:89], v[88:89], v[88:89], v[90:91]
	v_mov_b32_e32 v90, v102
	v_mov_b32_e32 v91, v98
	v_pk_mul_f32 v[92:93], v[92:93], v[92:93]
	s_nop 0
	v_pk_fma_f32 v[90:91], v[90:91], v[90:91], v[92:93]
	s_nop 0
	v_pk_add_f32 v[88:89], v[88:89], v[90:91]
	v_and_b32_e32 v90, 64, v163
	v_add_f32_e32 v88, v88, v89
	v_xor_b32_e32 v89, 16, v163
	v_add_u32_e32 v90, 64, v90
	v_cmp_lt_i32_e32 vcc, v89, v90
	s_nop 1
	v_cndmask_b32_e32 v89, v163, v89, vcc
	v_lshlrev_b32_e32 v89, 2, v89
	v_mov_b32_e32 v89, v88
	s_nop 1
	v_permlane16_swap_b32_e32 v88, v89
	s_waitcnt lgkmcnt(0)
	v_add_f32_e32 v88, v88, v89
	v_xor_b32_e32 v89, 32, v163
	v_cmp_lt_i32_e32 vcc, v89, v90
	s_nop 1
	v_cndmask_b32_e32 v89, v163, v89, vcc
	v_lshlrev_b32_e32 v89, 2, v89
	v_mov_b32_e32 v89, v88
	s_nop 1
	v_permlane32_swap_b32_e32 v88, v89
	s_waitcnt lgkmcnt(0)
	v_add_f32_e32 v88, v88, v89
	v_max_f32_e32 v89, v120, v120
	v_max_f32_e32 v120, v89, v88

; __device__ __forceinline__ float sq4(const f32x4& v) { return (v[0] * v[0] + v[1] * v[1]) + (v[2] * v[2] + v[3] * v[3]); }
;     __device__ __forceinline__ void operator()(const f32x4 (&acc)[2][2][4][2], const Unit& u, int wr, int wc, int fr, int fq) const {
;     ...
;                 if (reg <= 1) { float s = sq4(v0) + sq4(v1); s += __shfl_xor(s, 16); s += __shfl_xor(s, 32); mx[bj] = fmaxf(mx[bj], s); }
.LBB0_119:
	v_mov_b32_e32 v82, v95
	v_mov_b32_e32 v83, v91
	v_mov_b32_e32 v80, v94
	v_mov_b32_e32 v81, v90
	v_pk_mul_f32 v[82:83], v[82:83], v[82:83]
	v_mov_b32_e32 v84, v97
	v_mov_b32_e32 v85, v93
	v_pk_fma_f32 v[80:81], v[80:81], v[80:81], v[82:83]
	v_mov_b32_e32 v82, v96
	v_mov_b32_e32 v83, v92
	v_pk_mul_f32 v[84:85], v[84:85], v[84:85]
	s_nop 0
	v_pk_fma_f32 v[82:83], v[82:83], v[82:83], v[84:85]
	s_nop 0
	v_pk_add_f32 v[80:81], v[80:81], v[82:83]
	v_and_b32_e32 v82, 64, v163
	v_add_f32_e32 v80, v80, v81
	v_xor_b32_e32 v81, 16, v163
	v_add_u32_e32 v82, 64, v82
	v_cmp_lt_i32_e32 vcc, v81, v82
	s_nop 1
	v_cndmask_b32_e32 v81, v163, v81, vcc
	v_lshlrev_b32_e32 v81, 2, v81
	v_mov_b32_e32 v81, v80
	s_nop 1
	v_permlane16_swap_b32_e32 v80, v81
	s_waitcnt lgkmcnt(0)
	v_add_f32_e32 v80, v80, v81
	v_xor_b32_e32 v81, 32, v163
	v_cmp_lt_i32_e32 vcc, v81, v82
	s_nop 1
	v_cndmask_b32_e32 v81, v163, v81, vcc
	v_lshlrev_b32_e32 v81, 2, v81
	v_mov_b32_e32 v81, v80
	s_nop 1
	v_permlane32_swap_b32_e32 v80, v81
	s_waitcnt lgkmcnt(0)
	v_add_f32_e32 v80, v80, v81
	v_max_f32_e32 v81, v121, v121
	v_max_f32_e32 v121, v81, v80

; __device__ __forceinline__ float sq4(const f32x4& v) { return (v[0] * v[0] + v[1] * v[1]) + (v[2] * v[2] + v[3] * v[3]); }
;     __device__ __forceinline__ void operator()(const f32x4 (&acc)[2][2][4][2], const Unit& u, int wr, int wc, int fr, int fq) const {
;     ...
;                 if (reg <= 1) { float s = sq4(v0) + sq4(v1); s += __shfl_xor(s, 16); s += __shfl_xor(s, 32); mx[bj] = fmaxf(mx[bj], s); }
.LBB0_123:
	v_mov_b32_e32 v74, v85
	v_mov_b32_e32 v75, v81
	v_mov_b32_e32 v72, v84
	v_mov_b32_e32 v73, v80
	v_pk_mul_f32 v[74:75], v[74:75], v[74:75]
	v_mov_b32_e32 v76, v87
	v_mov_b32_e32 v77, v83
	v_pk_fma_f32 v[72:73], v[72:73], v[72:73], v[74:75]
	v_mov_b32_e32 v74, v86
	v_mov_b32_e32 v75, v82
	v_pk_mul_f32 v[76:77], v[76:77], v[76:77]
	s_nop 0
	v_pk_fma_f32 v[74:75], v[74:75], v[74:75], v[76:77]
	s_nop 0
	v_pk_add_f32 v[72:73], v[72:73], v[74:75]
	v_and_b32_e32 v74, 64, v163
	v_add_f32_e32 v72, v72, v73
	v_xor_b32_e32 v73, 16, v163
	v_add_u32_e32 v74, 64, v74
	v_cmp_lt_i32_e32 vcc, v73, v74
	s_nop 1
	v_cndmask_b32_e32 v73, v163, v73, vcc
	v_lshlrev_b32_e32 v73, 2, v73
	v_mov_b32_e32 v73, v72
	s_nop 1
	v_permlane16_swap_b32_e32 v72, v73
	s_waitcnt lgkmcnt(0)
	v_add_f32_e32 v72, v72, v73
	v_xor_b32_e32 v73, 32, v163
	v_cmp_lt_i32_e32 vcc, v73, v74
	s_nop 1
	v_cndmask_b32_e32 v73, v163, v73, vcc
	v_lshlrev_b32_e32 v73, 2, v73
	v_mov_b32_e32 v73, v72
	s_nop 1
	v_permlane32_swap_b32_e32 v72, v73
	s_waitcnt lgkmcnt(0)
	v_add_f32_e32 v72, v72, v73
	v_max_f32_e32 v73, v120, v120
	v_max_f32_e32 v120, v73, v72

; __device__ __forceinline__ float sq4(const f32x4& v) { return (v[0] * v[0] + v[1] * v[1]) + (v[2] * v[2] + v[3] * v[3]); }
;     __device__ __forceinline__ void operator()(const f32x4 (&acc)[2][2][4][2], const Unit& u, int wr, int wc, int fr, int fq) const {
;     ...
;                 if (reg <= 1) { float s = sq4(v0) + sq4(v1); s += __shfl_xor(s, 16); s += __shfl_xor(s, 32); mx[bj] = fmaxf(mx[bj], s); }
.LBB0_127:
	v_mov_b32_e32 v66, v79
	v_mov_b32_e32 v67, v75
	v_mov_b32_e32 v64, v78
	v_mov_b32_e32 v65, v74
	v_pk_mul_f32 v[66:67], v[66:67], v[66:67]
	v_mov_b32_e32 v68, v81
	v_mov_b32_e32 v69, v77
	v_pk_fma_f32 v[64:65], v[64:65], v[64:65], v[66:67]
	v_mov_b32_e32 v66, v80
	v_mov_b32_e32 v67, v76
	v_pk_mul_f32 v[68:69], v[68:69], v[68:69]
	s_nop 0
	v_pk_fma_f32 v[66:67], v[66:67], v[66:67], v[68:69]
	s_nop 0
	v_pk_add_f32 v[64:65], v[64:65], v[66:67]
	v_and_b32_e32 v66, 64, v163
	v_add_f32_e32 v64, v64, v65
	v_xor_b32_e32 v65, 16, v163
	v_add_u32_e32 v66, 64, v66
	v_cmp_lt_i32_e32 vcc, v65, v66
	s_nop 1
	v_cndmask_b32_e32 v65, v163, v65, vcc
	v_lshlrev_b32_e32 v65, 2, v65
	v_mov_b32_e32 v65, v64
	s_nop 1
	v_permlane16_swap_b32_e32 v64, v65
	s_waitcnt lgkmcnt(0)
	v_add_f32_e32 v64, v64, v65
	v_xor_b32_e32 v65, 32, v163
	v_cmp_lt_i32_e32 vcc, v65, v66
	s_nop 1
	v_cndmask_b32_e32 v65, v163, v65, vcc
	v_lshlrev_b32_e32 v65, 2, v65
	v_mov_b32_e32 v65, v64
	s_nop 1
	v_permlane32_swap_b32_e32 v64, v65
	s_waitcnt lgkmcnt(0)
	v_add_f32_e32 v64, v64, v65
	v_max_f32_e32 v65, v121, v121
	v_max_f32_e32 v121, v65, v64

; __device__ __forceinline__ float sq4(const f32x4& v) { return (v[0] * v[0] + v[1] * v[1]) + (v[2] * v[2] + v[3] * v[3]); }
;     __device__ __forceinline__ void operator()(const f32x4 (&acc)[2][2][4][2], const Unit& u, int wr, int wc, int fr, int fq) const {
;     ...
;                 if (reg <= 1) { float s = sq4(v0) + sq4(v1); s += __shfl_xor(s, 16); s += __shfl_xor(s, 32); mx[bj] = fmaxf(mx[bj], s); }
.LBB0_131:
	v_mov_b32_e32 v58, v69
	v_mov_b32_e32 v59, v65
	v_mov_b32_e32 v56, v68
	v_mov_b32_e32 v57, v64
	v_pk_mul_f32 v[58:59], v[58:59], v[58:59]
	v_mov_b32_e32 v60, v71
	v_mov_b32_e32 v61, v67
	v_pk_fma_f32 v[56:57], v[56:57], v[56:57], v[58:59]
	v_mov_b32_e32 v58, v70
	v_mov_b32_e32 v59, v66
	v_pk_mul_f32 v[60:61], v[60:61], v[60:61]
	s_nop 0
	v_pk_fma_f32 v[58:59], v[58:59], v[58:59], v[60:61]
	s_nop 0
	v_pk_add_f32 v[56:57], v[56:57], v[58:59]
	v_and_b32_e32 v58, 64, v163
	v_add_f32_e32 v56, v56, v57
	v_xor_b32_e32 v57, 16, v163
	v_add_u32_e32 v58, 64, v58
	v_cmp_lt_i32_e32 vcc, v57, v58
	s_nop 1
	v_cndmask_b32_e32 v57, v163, v57, vcc
	v_lshlrev_b32_e32 v57, 2, v57
	v_mov_b32_e32 v57, v56
	s_nop 1
	v_permlane16_swap_b32_e32 v56, v57
	s_waitcnt lgkmcnt(0)
	v_add_f32_e32 v56, v56, v57
	v_xor_b32_e32 v57, 32, v163
	v_cmp_lt_i32_e32 vcc, v57, v58
	s_nop 1
	v_cndmask_b32_e32 v57, v163, v57, vcc
	v_lshlrev_b32_e32 v57, 2, v57
	v_mov_b32_e32 v57, v56
	s_nop 1
	v_permlane32_swap_b32_e32 v56, v57
	s_waitcnt lgkmcnt(0)
	v_add_f32_e32 v56, v56, v57
	v_max_f32_e32 v57, v120, v120
	v_max_f32_e32 v120, v57, v56

; __device__ __forceinline__ float sq4(const f32x4& v) { return (v[0] * v[0] + v[1] * v[1]) + (v[2] * v[2] + v[3] * v[3]); }
;     __device__ __forceinline__ void operator()(const f32x4 (&acc)[2][2][4][2], const Unit& u, int wr, int wc, int fr, int fq) const {
;     ...
;                 if (reg <= 1) { float s = sq4(v0) + sq4(v1); s += __shfl_xor(s, 16); s += __shfl_xor(s, 32); mx[bj] = fmaxf(mx[bj], s); }
.LBB0_135:
	v_mov_b32_e32 v50, v63
	v_mov_b32_e32 v51, v59
	v_mov_b32_e32 v48, v62
	v_mov_b32_e32 v49, v58
	v_pk_mul_f32 v[50:51], v[50:51], v[50:51]
	v_mov_b32_e32 v52, v65
	v_mov_b32_e32 v53, v61
	v_pk_fma_f32 v[48:49], v[48:49], v[48:49], v[50:51]
	v_mov_b32_e32 v50, v64
	v_mov_b32_e32 v51, v60
	v_pk_mul_f32 v[52:53], v[52:53], v[52:53]
	s_nop 0
	v_pk_fma_f32 v[50:51], v[50:51], v[50:51], v[52:53]
	s_nop 0
	v_pk_add_f32 v[48:49], v[48:49], v[50:51]
	v_and_b32_e32 v50, 64, v163
	v_add_f32_e32 v48, v48, v49
	v_xor_b32_e32 v49, 16, v163
	v_add_u32_e32 v50, 64, v50
	v_cmp_lt_i32_e32 vcc, v49, v50
	s_nop 1
	v_cndmask_b32_e32 v49, v163, v49, vcc
	v_lshlrev_b32_e32 v49, 2, v49
	v_mov_b32_e32 v49, v48
	s_nop 1
	v_permlane16_swap_b32_e32 v48, v49
	s_waitcnt lgkmcnt(0)
	v_add_f32_e32 v48, v48, v49
	v_xor_b32_e32 v49, 32, v163
	v_cmp_lt_i32_e32 vcc, v49, v50
	s_nop 1
	v_cndmask_b32_e32 v49, v163, v49, vcc
	v_lshlrev_b32_e32 v49, 2, v49
	v_mov_b32_e32 v49, v48
	s_nop 1
	v_permlane32_swap_b32_e32 v48, v49
	s_waitcnt lgkmcnt(0)
	v_add_f32_e32 v48, v48, v49
	v_max_f32_e32 v49, v121, v121
	v_max_f32_e32 v121, v49, v48

; __device__ __forceinline__ float sq4(const f32x4& v) { return (v[0] * v[0] + v[1] * v[1]) + (v[2] * v[2] + v[3] * v[3]); }
;     __device__ __forceinline__ void operator()(const f32x4 (&acc)[2][2][4][2], const Unit& u, int wr, int wc, int fr, int fq) const {
;     ...
;                 if (reg <= 1) { float s = sq4(v0) + sq4(v1); s += __shfl_xor(s, 16); s += __shfl_xor(s, 32); mx[bj] = fmaxf(mx[bj], s); }
.LBB0_139:
	v_mov_b32_e32 v42, v53
	v_mov_b32_e32 v43, v49
	v_mov_b32_e32 v40, v52
	v_mov_b32_e32 v41, v48
	v_pk_mul_f32 v[42:43], v[42:43], v[42:43]
	v_mov_b32_e32 v44, v55
	v_mov_b32_e32 v45, v51
	v_pk_fma_f32 v[40:41], v[40:41], v[40:41], v[42:43]
	v_mov_b32_e32 v42, v54
	v_mov_b32_e32 v43, v50
	v_pk_mul_f32 v[44:45], v[44:45], v[44:45]
	s_nop 0
	v_pk_fma_f32 v[42:43], v[42:43], v[42:43], v[44:45]
	s_nop 0
	v_pk_add_f32 v[40:41], v[40:41], v[42:43]
	v_and_b32_e32 v42, 64, v163
	v_add_f32_e32 v40, v40, v41
	v_xor_b32_e32 v41, 16, v163
	v_add_u32_e32 v42, 64, v42
	v_cmp_lt_i32_e32 vcc, v41, v42
	s_nop 1
	v_cndmask_b32_e32 v41, v163, v41, vcc
	v_lshlrev_b32_e32 v41, 2, v41
	v_mov_b32_e32 v41, v40
	s_nop 1
	v_permlane16_swap_b32_e32 v40, v41
	s_waitcnt lgkmcnt(0)
	v_add_f32_e32 v40, v40, v41
	v_xor_b32_e32 v41, 32, v163
	v_cmp_lt_i32_e32 vcc, v41, v42
	s_nop 1
	v_cndmask_b32_e32 v41, v163, v41, vcc
	v_lshlrev_b32_e32 v41, 2, v41
	v_mov_b32_e32 v41, v40
	s_nop 1
	v_permlane32_swap_b32_e32 v40, v41
	s_waitcnt lgkmcnt(0)
	v_add_f32_e32 v40, v40, v41
	v_max_f32_e32 v41, v120, v120
	v_max_f32_e32 v120, v41, v40

; __device__ __forceinline__ float sq4(const f32x4& v) { return (v[0] * v[0] + v[1] * v[1]) + (v[2] * v[2] + v[3] * v[3]); }
;     __device__ __forceinline__ void operator()(const f32x4 (&acc)[2][2][4][2], const Unit& u, int wr, int wc, int fr, int fq) const {
;     ...
;                 if (reg <= 1) { float s = sq4(v0) + sq4(v1); s += __shfl_xor(s, 16); s += __shfl_xor(s, 32); mx[bj] = fmaxf(mx[bj], s); }
.LBB0_143:
	v_mov_b32_e32 v34, v47
	v_mov_b32_e32 v35, v43
	v_mov_b32_e32 v32, v46
	v_mov_b32_e32 v33, v42
	v_pk_mul_f32 v[34:35], v[34:35], v[34:35]
	v_mov_b32_e32 v36, v49
	v_mov_b32_e32 v37, v45
	v_pk_fma_f32 v[32:33], v[32:33], v[32:33], v[34:35]
	v_mov_b32_e32 v34, v48
	v_mov_b32_e32 v35, v44
	v_pk_mul_f32 v[36:37], v[36:37], v[36:37]
	s_nop 0
	v_pk_fma_f32 v[34:35], v[34:35], v[34:35], v[36:37]
	s_nop 0
	v_pk_add_f32 v[32:33], v[32:33], v[34:35]
	v_and_b32_e32 v34, 64, v163
	v_add_f32_e32 v32, v32, v33
	v_xor_b32_e32 v33, 16, v163
	v_add_u32_e32 v34, 64, v34
	v_cmp_lt_i32_e32 vcc, v33, v34
	s_nop 1
	v_cndmask_b32_e32 v33, v163, v33, vcc
	v_lshlrev_b32_e32 v33, 2, v33
	v_mov_b32_e32 v33, v32
	s_nop 1
	v_permlane16_swap_b32_e32 v32, v33
	s_waitcnt lgkmcnt(0)
	v_add_f32_e32 v32, v32, v33
	v_xor_b32_e32 v33, 32, v163
	v_cmp_lt_i32_e32 vcc, v33, v34
	s_nop 1
	v_cndmask_b32_e32 v33, v163, v33, vcc
	v_lshlrev_b32_e32 v33, 2, v33
	v_mov_b32_e32 v33, v32
	s_nop 1
	v_permlane32_swap_b32_e32 v32, v33
	s_waitcnt lgkmcnt(0)
	v_add_f32_e32 v32, v32, v33
	v_max_f32_e32 v33, v121, v121
	v_max_f32_e32 v121, v33, v32

; __device__ __forceinline__ float sq4(const f32x4& v) { return (v[0] * v[0] + v[1] * v[1]) + (v[2] * v[2] + v[3] * v[3]); }
;     __device__ __forceinline__ void operator()(const f32x4 (&acc)[2][2][4][2], const Unit& u, int wr, int wc, int fr, int fq) const {
;     ...
;                 if (reg <= 1) { float s = sq4(v0) + sq4(v1); s += __shfl_xor(s, 16); s += __shfl_xor(s, 32); mx[bj] = fmaxf(mx[bj], s); }
.LBB0_147:
	v_mov_b32_e32 v26, v37
	v_mov_b32_e32 v27, v33
	v_mov_b32_e32 v24, v36
	v_mov_b32_e32 v25, v32
	v_pk_mul_f32 v[26:27], v[26:27], v[26:27]
	v_mov_b32_e32 v28, v39
	v_mov_b32_e32 v29, v35
	v_pk_fma_f32 v[24:25], v[24:25], v[24:25], v[26:27]
	v_mov_b32_e32 v26, v38
	v_mov_b32_e32 v27, v34
	v_pk_mul_f32 v[28:29], v[28:29], v[28:29]
	s_nop 0
	v_pk_fma_f32 v[26:27], v[26:27], v[26:27], v[28:29]
	s_nop 0
	v_pk_add_f32 v[24:25], v[24:25], v[26:27]
	v_and_b32_e32 v26, 64, v163
	v_add_f32_e32 v24, v24, v25
	v_xor_b32_e32 v25, 16, v163
	v_add_u32_e32 v26, 64, v26
	v_cmp_lt_i32_e32 vcc, v25, v26
	s_nop 1
	v_cndmask_b32_e32 v25, v163, v25, vcc
	v_lshlrev_b32_e32 v25, 2, v25
	v_mov_b32_e32 v25, v24
	s_nop 1
	v_permlane16_swap_b32_e32 v24, v25
	s_waitcnt lgkmcnt(0)
	v_add_f32_e32 v24, v24, v25
	v_xor_b32_e32 v25, 32, v163
	v_cmp_lt_i32_e32 vcc, v25, v26
	s_nop 1
	v_cndmask_b32_e32 v25, v163, v25, vcc
	v_lshlrev_b32_e32 v25, 2, v25
	v_mov_b32_e32 v25, v24
	s_nop 1
	v_permlane32_swap_b32_e32 v24, v25
	s_waitcnt lgkmcnt(0)
	v_add_f32_e32 v24, v24, v25
	v_max_f32_e32 v25, v120, v120
	v_max_f32_e32 v120, v25, v24

; __device__ __forceinline__ float sq4(const f32x4& v) { return (v[0] * v[0] + v[1] * v[1]) + (v[2] * v[2] + v[3] * v[3]); }
;     __device__ __forceinline__ void operator()(const f32x4 (&acc)[2][2][4][2], const Unit& u, int wr, int wc, int fr, int fq) const {
;     ...
;                 if (reg <= 1) { float s = sq4(v0) + sq4(v1); s += __shfl_xor(s, 16); s += __shfl_xor(s, 32); mx[bj] = fmaxf(mx[bj], s); }
.LBB0_151:
	v_mov_b32_e32 v18, v31
	v_mov_b32_e32 v19, v27
	v_mov_b32_e32 v16, v30
	v_mov_b32_e32 v17, v26
	v_pk_mul_f32 v[18:19], v[18:19], v[18:19]
	v_mov_b32_e32 v20, v33
	v_mov_b32_e32 v21, v29
	v_pk_fma_f32 v[16:17], v[16:17], v[16:17], v[18:19]
	v_mov_b32_e32 v18, v32
	v_mov_b32_e32 v19, v28
	v_pk_mul_f32 v[20:21], v[20:21], v[20:21]
	s_nop 0
	v_pk_fma_f32 v[18:19], v[18:19], v[18:19], v[20:21]
	s_nop 0
	v_pk_add_f32 v[16:17], v[16:17], v[18:19]
	v_and_b32_e32 v18, 64, v163
	v_add_f32_e32 v16, v16, v17
	v_xor_b32_e32 v17, 16, v163
	v_add_u32_e32 v18, 64, v18
	v_cmp_lt_i32_e32 vcc, v17, v18
	s_nop 1
	v_cndmask_b32_e32 v17, v163, v17, vcc
	v_lshlrev_b32_e32 v17, 2, v17
	v_mov_b32_e32 v17, v16
	s_nop 1
	v_permlane16_swap_b32_e32 v16, v17
	s_waitcnt lgkmcnt(0)
	v_add_f32_e32 v16, v16, v17
	v_xor_b32_e32 v17, 32, v163
	v_cmp_lt_i32_e32 vcc, v17, v18
	s_nop 1
	v_cndmask_b32_e32 v17, v163, v17, vcc
	v_lshlrev_b32_e32 v17, 2, v17
	v_mov_b32_e32 v17, v16
	s_nop 1
	v_permlane32_swap_b32_e32 v16, v17
	s_waitcnt lgkmcnt(0)
	v_add_f32_e32 v16, v16, v17
	v_max_f32_e32 v17, v121, v121
	v_max_f32_e32 v121, v17, v16

; __device__ __forceinline__ float sq4(const f32x4& v) { return (v[0] * v[0] + v[1] * v[1]) + (v[2] * v[2] + v[3] * v[3]); }
;     __device__ __forceinline__ void operator()(const f32x4 (&acc)[2][2][4][2], const Unit& u, int wr, int wc, int fr, int fq) const {
;     ...
;                 if (reg <= 1) { float s = sq4(v0) + sq4(v1); s += __shfl_xor(s, 16); s += __shfl_xor(s, 32); mx[bj] = fmaxf(mx[bj], s); }
.LBB0_155:
	v_mov_b32_e32 v10, v21
	v_mov_b32_e32 v11, v17
	v_mov_b32_e32 v8, v20
	v_mov_b32_e32 v9, v16
	v_pk_mul_f32 v[10:11], v[10:11], v[10:11]
	v_mov_b32_e32 v12, v23
	v_mov_b32_e32 v13, v19
	v_pk_fma_f32 v[8:9], v[8:9], v[8:9], v[10:11]
	v_mov_b32_e32 v10, v22
	v_mov_b32_e32 v11, v18
	v_pk_mul_f32 v[12:13], v[12:13], v[12:13]
	s_nop 0
	v_pk_fma_f32 v[10:11], v[10:11], v[10:11], v[12:13]
	s_nop 0
	v_pk_add_f32 v[8:9], v[8:9], v[10:11]
	v_and_b32_e32 v10, 64, v163
	v_add_f32_e32 v8, v8, v9
	v_xor_b32_e32 v9, 16, v163
	v_add_u32_e32 v10, 64, v10
	v_cmp_lt_i32_e32 vcc, v9, v10
	s_nop 1
	v_cndmask_b32_e32 v9, v163, v9, vcc
	v_lshlrev_b32_e32 v9, 2, v9
	v_mov_b32_e32 v9, v8
	s_nop 1
	v_permlane16_swap_b32_e32 v8, v9
	s_waitcnt lgkmcnt(0)
	v_add_f32_e32 v8, v8, v9
	v_xor_b32_e32 v9, 32, v163
	v_cmp_lt_i32_e32 vcc, v9, v10
	s_nop 1
	v_cndmask_b32_e32 v9, v163, v9, vcc
	v_lshlrev_b32_e32 v9, 2, v9
	v_mov_b32_e32 v9, v8
	s_nop 1
	v_permlane32_swap_b32_e32 v8, v9
	s_waitcnt lgkmcnt(0)
	v_add_f32_e32 v8, v8, v9
	v_max_f32_e32 v9, v120, v120
	v_max_f32_e32 v120, v9, v8

; __device__ __forceinline__ float sq4(const f32x4& v) { return (v[0] * v[0] + v[1] * v[1]) + (v[2] * v[2] + v[3] * v[3]); }
;     __device__ __forceinline__ void operator()(const f32x4 (&acc)[2][2][4][2], const Unit& u, int wr, int wc, int fr, int fq) const {
;     ...
;                 if (reg <= 1) { float s = sq4(v0) + sq4(v1); s += __shfl_xor(s, 16); s += __shfl_xor(s, 32); mx[bj] = fmaxf(mx[bj], s); }
.LBB0_159:
	v_mov_b32_e32 v2, v15
	v_mov_b32_e32 v3, v11
	v_mov_b32_e32 v0, v14
	v_mov_b32_e32 v1, v10
	v_pk_mul_f32 v[2:3], v[2:3], v[2:3]
	v_mov_b32_e32 v4, v17
	v_mov_b32_e32 v5, v13
	v_pk_fma_f32 v[0:1], v[0:1], v[0:1], v[2:3]
	v_mov_b32_e32 v2, v16
	v_mov_b32_e32 v3, v12
	v_pk_mul_f32 v[4:5], v[4:5], v[4:5]
	s_nop 0
	v_pk_fma_f32 v[2:3], v[2:3], v[2:3], v[4:5]
	s_nop 0
	v_pk_add_f32 v[0:1], v[0:1], v[2:3]
	v_and_b32_e32 v2, 64, v163
	v_add_f32_e32 v0, v0, v1
	v_xor_b32_e32 v1, 16, v163
	v_add_u32_e32 v2, 64, v2
	v_cmp_lt_i32_e32 vcc, v1, v2
	s_nop 1
	v_cndmask_b32_e32 v1, v163, v1, vcc
	v_lshlrev_b32_e32 v1, 2, v1
	v_mov_b32_e32 v1, v0
	s_nop 1
	v_permlane16_swap_b32_e32 v0, v1
	s_waitcnt lgkmcnt(0)
	v_add_f32_e32 v0, v0, v1
	v_xor_b32_e32 v1, 32, v163
	v_cmp_lt_i32_e32 vcc, v1, v2
	s_nop 1
	v_cndmask_b32_e32 v1, v163, v1, vcc
	v_lshlrev_b32_e32 v1, 2, v1
	v_mov_b32_e32 v1, v0
	s_nop 1
	v_permlane32_swap_b32_e32 v0, v1
	s_waitcnt lgkmcnt(0)
	v_add_f32_e32 v0, v0, v1
	v_max_f32_e32 v1, v121, v121
	v_max_f32_e32 v121, v1, v0
